# prologue de-serialisation: prep_task raw-row staging issues its five global loads together (one wait) instead of five load-wait-write rounds
# baseline (speedup 1.0000x reference)
.LBB0_726:
	v_ashrrev_i32_e32 v120, 6, v6
	s_movk_i32 s10, 0x80
	v_add3_u32 v121, v120, s7, 0
	v_cmp_gt_u32_e32 vcc, s24, v121
	v_mov_b32_e32 v126, 0
	s_and_saveexec_b64 s[46:47], vcc
	v_or_b32_e32 v7, s6, v121
	v_mov_b64_e32 v[8:9], s[18:19]
	v_mad_i64_i32 v[8:9], s[48:49], v7, s8, v[8:9]
	v_lshl_add_u64 v[8:9], v[8:9], 0, v[0:1]
	v_add_co_u32_e32 v8, vcc, 0x1000, v8
	s_nop 1
	v_addc_co_u32_e32 v9, vcc, 0, v9, vcc
	global_load_ushort v126, v[8:9], off offset:2592
	s_or_b64 exec, exec, s[46:47]
	v_add3_u32 v122, v120, s7, 8
	v_cmp_gt_u32_e32 vcc, s24, v122
	v_mov_b32_e32 v127, 0
	s_and_saveexec_b64 s[46:47], vcc
	v_or_b32_e32 v7, s6, v122
	v_mov_b64_e32 v[8:9], s[18:19]
	v_mad_i64_i32 v[8:9], s[48:49], v7, s8, v[8:9]
	v_lshl_add_u64 v[8:9], v[8:9], 0, v[0:1]
	v_add_co_u32_e32 v8, vcc, 0x1000, v8
	s_nop 1
	v_addc_co_u32_e32 v9, vcc, 0, v9, vcc
	global_load_ushort v127, v[8:9], off offset:2592
	s_or_b64 exec, exec, s[46:47]
	v_add3_u32 v123, v120, s7, 16
	v_cmp_gt_u32_e32 vcc, s24, v123
	v_mov_b32_e32 v128, 0
	s_and_saveexec_b64 s[46:47], vcc
	v_or_b32_e32 v7, s6, v123
	v_mov_b64_e32 v[8:9], s[18:19]
	v_mad_i64_i32 v[8:9], s[48:49], v7, s8, v[8:9]
	v_lshl_add_u64 v[8:9], v[8:9], 0, v[0:1]
	v_add_co_u32_e32 v8, vcc, 0x1000, v8
	s_nop 1
	v_addc_co_u32_e32 v9, vcc, 0, v9, vcc
	global_load_ushort v128, v[8:9], off offset:2592
	s_or_b64 exec, exec, s[46:47]
	v_add3_u32 v124, v120, s7, 24
	v_cmp_gt_u32_e32 vcc, s24, v124
	v_mov_b32_e32 v129, 0
	s_and_saveexec_b64 s[46:47], vcc
	v_or_b32_e32 v7, s6, v124
	v_mov_b64_e32 v[8:9], s[18:19]
	v_mad_i64_i32 v[8:9], s[48:49], v7, s8, v[8:9]
	v_lshl_add_u64 v[8:9], v[8:9], 0, v[0:1]
	v_add_co_u32_e32 v8, vcc, 0x1000, v8
	s_nop 1
	v_addc_co_u32_e32 v9, vcc, 0, v9, vcc
	global_load_ushort v129, v[8:9], off offset:2592
	s_or_b64 exec, exec, s[46:47]
	v_add3_u32 v125, v120, s7, 32
	v_cmp_gt_u32_e32 vcc, s24, v125
	v_cmp_gt_i32_e64 s[44:45], s10, v6
	v_mov_b32_e32 v130, 0
	s_and_b64 vcc, vcc, s[44:45]
	s_and_saveexec_b64 s[46:47], vcc
	v_or_b32_e32 v7, s6, v125
	v_mov_b64_e32 v[8:9], s[18:19]
	v_mad_i64_i32 v[8:9], s[48:49], v7, s8, v[8:9]
	v_lshl_add_u64 v[8:9], v[8:9], 0, v[0:1]
	v_add_co_u32_e32 v8, vcc, 0x1000, v8
	s_nop 1
	v_addc_co_u32_e32 v9, vcc, 0, v9, vcc
	global_load_ushort v130, v[8:9], off offset:2592
	s_or_b64 exec, exec, s[46:47]
	s_waitcnt vmcnt(4)
	v_lshlrev_b32_e32 v126, 16, v126
	ds_write_b32 v5, v126
	s_waitcnt vmcnt(3)
	v_lshlrev_b32_e32 v127, 16, v127
	ds_write_b32 v5, v127 offset:2048
	s_waitcnt vmcnt(2)
	v_lshlrev_b32_e32 v128, 16, v128
	ds_write_b32 v5, v128 offset:4096
	s_waitcnt vmcnt(1)
	v_lshlrev_b32_e32 v129, 16, v129
	ds_write_b32 v5, v129 offset:6144
	s_waitcnt vmcnt(0)
	v_lshlrev_b32_e32 v130, 16, v130
	v_cmp_gt_i32_e32 vcc, s10, v6
	s_and_saveexec_b64 s[46:47], vcc
	ds_write_b32 v5, v130 offset:8192
	s_or_b64 exec, exec, s[46:47]
